# attention tile body rewritten: QK accumulators seeded with -m block (32 v_sub per tile removed), in-place exp2 with incremental row sum, 3-deep K-fragment register ring; same lazy-rescale rule
# speedup vs baseline: 1.0387x; 1.0143x over previous
.LBB0_879:
	s_mul_i32 s9, s54, s30
	s_cmpk_gt_i32 s9, 0x7ff
	s_mov_b32 s14, 5
	s_cbranch_scc1 .LBB0_894
	s_bitcmp0_b32 s54, 0
	s_cselect_b32 s8, s2, s17
	s_add_i32 s9, s8, s9
	s_cmpk_gt_i32 s9, 0x7ff
	s_mov_b32 s14, 7
	s_cbranch_scc1 .LBB0_894
	s_ashr_i32 s12, s9, 6
	s_and_b32 s15, s9, 7
	s_lshr_b32 s9, s9, 2
	s_sub_i32 s14, 31, s12
	s_and_b32 s9, s9, 14
	v_add_u32_e32 v206, s9, v200
	s_lshl_b32 s9, s15, 12
	s_lshl_b32 s55, s14, 7
	s_add_i32 s55, s55, s9
	s_lshr_b32 s9, s55, 8
	s_and_b32 s9, s9, 0xfffff0
	v_add_u32_e32 v172, s9, v206
	s_lshl_b32 s9, s14, 2
	v_lshlrev_b32_e32 v1, 7, v172
	s_and_b32 s9, s9, 0x7c
	v_or3_b32 v1, v1, s9, v201
	v_mad_i64_i32 v[2:3], s[12:13], v1, s36, v[162:163]
	v_add_co_u32_e32 v4, vcc, s37, v2
	global_load_dwordx4 v[98:101], v[2:3], off
	global_load_dwordx4 v[102:105], v[2:3], off offset:1024
	global_load_dwordx4 v[106:109], v[2:3], off offset:2048
	global_load_dwordx4 v[110:113], v[2:3], off offset:3072
	v_addc_co_u32_e32 v5, vcc, 0, v3, vcc
	v_add_co_u32_e32 v2, vcc, s40, v2
	s_lshl_b32 s56, s14, 1
	s_nop 0
	v_addc_co_u32_e32 v3, vcc, 0, v3, vcc
	global_load_dwordx4 v[114:117], v[4:5], off offset:1024
	global_load_dwordx4 v[118:121], v[4:5], off offset:2048
	global_load_dwordx4 v[122:125], v[2:3], off offset:-4096
	global_load_dwordx4 v[126:129], v[4:5], off offset:3072
	global_load_dwordx4 v[130:133], v[2:3], off
	global_load_dwordx4 v[134:137], v[2:3], off offset:1024
	global_load_dwordx4 v[138:141], v[2:3], off offset:2048
	global_load_dwordx4 v[142:145], v[2:3], off offset:3072
	s_mul_i32 s15, s15, 0x180000
	s_add_u32 s12, s42, s15
	s_addc_u32 s13, s43, 0
	v_readfirstlane_b32 s9, v203
	v_lshl_add_u64 v[2:3], s[12:13], 0, v[164:165]
	s_mov_b32 m0, s9
	v_readfirstlane_b32 s9, v204
	global_load_lds_dwordx4 v[2:3], off
	v_lshl_add_u64 v[2:3], s[12:13], 0, v[166:167]
	s_mov_b32 m0, s9
	v_readfirstlane_b32 s9, v205
	global_load_lds_dwordx4 v[2:3], off
	v_lshl_add_u64 v[2:3], s[12:13], 0, v[168:169]
	s_mov_b32 m0, s9
	s_add_i32 s8, s3, s8
	global_load_lds_dwordx4 v[2:3], off
	s_and_b32 s8, s8, 7
	v_mov_b32_e32 v14, v0
	v_mov_b32_e32 v15, v0
	s_mul_i32 s8, s8, 0x180000
	v_mov_b32_e32 v1, v0
	v_mov_b32_e32 v2, v0
	v_mov_b32_e32 v3, v0
	v_mov_b32_e32 v4, v0
	v_mov_b32_e32 v5, v0
	v_mov_b32_e32 v6, v0
	v_mov_b32_e32 v7, v0
	v_mov_b32_e32 v8, v0
	v_mov_b32_e32 v9, v0
	v_mov_b32_e32 v10, v0
	v_mov_b32_e32 v11, v0
	v_mov_b32_e32 v12, v0
	v_mov_b32_e32 v13, v0
	v_mov_b64_e32 v[64:65], v[14:15]
	v_mov_b64_e32 v[48:49], v[14:15]
	v_mov_b64_e32 v[32:33], v[14:15]
	s_add_u32 s8, s28, s8
	v_mov_b64_e32 v[62:63], v[12:13]
	v_mov_b64_e32 v[60:61], v[10:11]
	v_mov_b64_e32 v[58:59], v[8:9]
	v_mov_b64_e32 v[56:57], v[6:7]
	v_mov_b64_e32 v[54:55], v[4:5]
	v_mov_b64_e32 v[52:53], v[2:3]
	v_mov_b64_e32 v[50:51], v[0:1]
	v_mov_b64_e32 v[46:47], v[12:13]
	v_mov_b64_e32 v[44:45], v[10:11]
	v_mov_b64_e32 v[42:43], v[8:9]
	v_mov_b64_e32 v[40:41], v[6:7]
	v_mov_b64_e32 v[38:39], v[4:5]
	v_mov_b64_e32 v[36:37], v[2:3]
	v_mov_b64_e32 v[34:35], v[0:1]
	v_mov_b64_e32 v[30:31], v[12:13]
	v_mov_b64_e32 v[28:29], v[10:11]
	v_mov_b64_e32 v[26:27], v[8:9]
	v_mov_b64_e32 v[24:25], v[6:7]
	v_mov_b64_e32 v[22:23], v[4:5]
	v_mov_b64_e32 v[20:21], v[2:3]
	v_mov_b64_e32 v[18:19], v[0:1]
	v_mov_b64_e32 v[16:17], v[14:15]
	s_mov_b32 s57, 0
	v_or_b32_e32 v207, s56, v202
	s_addc_u32 s9, s29, 0
	v_mov_b64_e32 v[210:211], 0
	v_mov_b64_e32 v[212:213], 0
	v_mov_b64_e32 v[214:215], 0
	v_mov_b64_e32 v[216:217], 0
	v_mov_b64_e32 v[218:219], 0
	v_mov_b64_e32 v[220:221], 0
	v_mov_b64_e32 v[222:223], 0
	v_mov_b64_e32 v[224:225], 0
	v_mov_b32_e32 v173, 0
	v_mov_b64_e32 v[14:15], v[12:13]
	v_mov_b64_e32 v[12:13], v[10:11]
	v_mov_b64_e32 v[10:11], v[8:9]
	v_mov_b64_e32 v[8:9], v[6:7]
	v_mov_b64_e32 v[6:7], v[4:5]
	v_mov_b64_e32 v[4:5], v[2:3]
	v_mov_b64_e32 v[2:3], v[0:1]
	s_waitcnt vmcnt(0) lgkmcnt(0)
	s_barrier
	s_branch .LBB0_884

.LBB0_884:
	v_add_u32_e32 v1, 0x6000, v203
	v_lshl_add_u64 v[174:175], s[8:9], 0, v[164:165]
	v_readfirstlane_b32 s12, v1
	v_add_u32_e32 v1, 0x8000, v203
	v_lshl_add_u64 v[66:67], v[174:175], 0, s[0:1]
	s_mov_b32 m0, s12
	v_lshl_add_u64 v[176:177], s[8:9], 0, v[170:171]
	v_readfirstlane_b32 s12, v1
	v_add_u32_e32 v1, 0xa000, v203
	global_load_lds_dwordx4 v[66:67], off
	v_lshl_add_u64 v[66:67], v[176:177], 0, s[0:1]
	s_mov_b32 m0, s12
	v_lshl_add_u64 v[178:179], s[8:9], 0, v[168:169]
	v_readfirstlane_b32 s12, v1
	global_load_lds_dwordx4 v[66:67], off
	v_lshl_add_u64 v[66:67], v[178:179], 0, s[0:1]
	s_mov_b32 m0, s12
	v_cmp_le_u32_e32 vcc, s57, v207
	global_load_lds_dwordx4 v[66:67], off
	s_and_saveexec_b64 s[12:13], vcc
	s_cbranch_execz .LBB0_888
	ds_read_b128 v[146:149], v198
	ds_read_b128 v[150:153], v198 offset:8192
	v_xor_b32_e32 v209, 0x20, v198
	ds_read_b128 v[246:249], v209
	ds_read_b128 v[250:253], v209 offset:8192
	v_xor_b32_e32 v190, 0x40, v198
	ds_read_b128 v[180:183], v190
	ds_read_b128 v[184:187], v190 offset:8192
	s_waitcnt lgkmcnt(4)
	v_mfma_f32_32x32x16_bf16 v[82:97], v[146:149], v[98:101], v[210:225]
	v_mfma_f32_32x32x16_bf16 v[66:81], v[150:153], v[98:101], v[210:225]
	v_xor_b32_e32 v209, 0x60, v198
	ds_read_b128 v[146:149], v209
	ds_read_b128 v[150:153], v209 offset:8192
	s_waitcnt lgkmcnt(4)
	v_mfma_f32_32x32x16_bf16 v[82:97], v[246:249], v[102:105], v[82:97]
	v_mfma_f32_32x32x16_bf16 v[66:81], v[250:253], v[102:105], v[66:81]
	v_xor_b32_e32 v190, 0x80, v198
	ds_read_b128 v[246:249], v190
	ds_read_b128 v[250:253], v190 offset:8192
	s_waitcnt lgkmcnt(4)
	v_mfma_f32_32x32x16_bf16 v[82:97], v[180:183], v[106:109], v[82:97]
	v_mfma_f32_32x32x16_bf16 v[66:81], v[184:187], v[106:109], v[66:81]
	v_xor_b32_e32 v209, 0xa0, v198
	ds_read_b128 v[180:183], v209
	ds_read_b128 v[184:187], v209 offset:8192
	s_waitcnt lgkmcnt(4)
	v_mfma_f32_32x32x16_bf16 v[82:97], v[146:149], v[110:113], v[82:97]
	v_mfma_f32_32x32x16_bf16 v[66:81], v[150:153], v[110:113], v[66:81]
	v_xor_b32_e32 v190, 0xc0, v198
	ds_read_b128 v[146:149], v190
	ds_read_b128 v[150:153], v190 offset:8192
	s_waitcnt lgkmcnt(4)
	v_mfma_f32_32x32x16_bf16 v[82:97], v[246:249], v[122:125], v[82:97]
	v_mfma_f32_32x32x16_bf16 v[66:81], v[250:253], v[122:125], v[66:81]
	v_xor_b32_e32 v209, 0xe0, v198
	ds_read_b128 v[246:249], v209
	ds_read_b128 v[250:253], v209 offset:8192
	s_waitcnt lgkmcnt(4)
	v_mfma_f32_32x32x16_bf16 v[82:97], v[180:183], v[114:117], v[82:97]
	v_mfma_f32_32x32x16_bf16 v[66:81], v[184:187], v[114:117], v[66:81]
	ds_read_b128 v[180:183], v199
	ds_read_b128 v[184:187], v199 offset:4096
	s_waitcnt lgkmcnt(4)
	v_mfma_f32_32x32x16_bf16 v[82:97], v[146:149], v[118:121], v[82:97]
	v_mfma_f32_32x32x16_bf16 v[66:81], v[150:153], v[118:121], v[66:81]
	v_xor_b32_e32 v209, 0x20, v199
	ds_read_b128 v[146:149], v209
	ds_read_b128 v[150:153], v209 offset:4096
	s_waitcnt lgkmcnt(4)
	v_mfma_f32_32x32x16_bf16 v[82:97], v[246:249], v[126:129], v[82:97]
	v_mfma_f32_32x32x16_bf16 v[66:81], v[250:253], v[126:129], v[66:81]
	v_xor_b32_e32 v190, 0x40, v199
	ds_read_b128 v[246:249], v190
	ds_read_b128 v[250:253], v190 offset:4096
	s_waitcnt lgkmcnt(4)
	v_mfma_f32_32x32x16_bf16 v[82:97], v[180:183], v[130:133], v[82:97]
	v_mfma_f32_32x32x16_bf16 v[66:81], v[184:187], v[130:133], v[66:81]
	v_xor_b32_e32 v209, 0x60, v199
	ds_read_b128 v[180:183], v209
	ds_read_b128 v[184:187], v209 offset:4096
	s_waitcnt lgkmcnt(4)
	v_mfma_f32_32x32x16_bf16 v[82:97], v[146:149], v[134:137], v[82:97]
	v_mfma_f32_32x32x16_bf16 v[66:81], v[150:153], v[134:137], v[66:81]
	s_waitcnt lgkmcnt(2)
	v_mfma_f32_32x32x16_bf16 v[82:97], v[246:249], v[138:141], v[82:97]
	v_mfma_f32_32x32x16_bf16 v[66:81], v[250:253], v[138:141], v[66:81]
	s_waitcnt lgkmcnt(0)
	v_mfma_f32_32x32x16_bf16 v[66:81], v[184:187], v[142:145], v[66:81]
	ds_read_b64_tr_b16 v[158:159], v188 offset:0
	ds_read_b64_tr_b16 v[160:161], v189 offset:0
	ds_read_b64_tr_b16 v[154:155], v192 offset:0
	ds_read_b64_tr_b16 v[156:157], v193 offset:0
	ds_read_b64_tr_b16 v[150:151], v194 offset:0
	ds_read_b64_tr_b16 v[152:153], v195 offset:0
	ds_read_b64_tr_b16 v[146:147], v196 offset:0
	ds_read_b64_tr_b16 v[148:149], v197 offset:0
	v_mfma_f32_32x32x16_bf16 v[82:97], v[180:183], v[142:145], v[82:97]
	s_nop 4
	v_max3_f32 v1, v66, v67, v68
	v_max3_f32 v180, v69, v70, v71
	v_max3_f32 v1, v1, v72, v73
	v_max3_f32 v180, v180, v74, v75
	v_max3_f32 v1, v1, v76, v77
	v_max3_f32 v180, v180, v78, v79
	v_max3_f32 v1, v1, v80, v81
	v_max3_f32 v181, v82, v83, v84
	v_max3_f32 v182, v85, v86, v87
	v_max3_f32 v181, v181, v88, v89
	v_max3_f32 v182, v182, v90, v91
	v_max3_f32 v181, v181, v92, v93
	v_max3_f32 v182, v182, v94, v95
	v_max3_f32 v181, v181, v96, v97
	v_max3_f32 v1, v1, v180, v181
	v_max_f32_e32 v1, v1, v182
	v_mov_b32_e32 v180, v1
	s_nop 1
	v_permlane32_swap_b32_e32 v1, v180
	v_max_f32_e32 v1, v1, v180
	s_cmp_eq_u32 s57, 0
	s_cbranch_scc1 .Latt_rare0
	v_cmp_lt_f32_e32 vcc, 0x41000000, v1
	s_cbranch_vccz .Latt_common0
.Latt_rare0:
	s_cmp_eq_u32 s57, 0
	s_cselect_b32 s71, 0xf149f2ca, 0
	v_max_f32_e64 v243, v1, s71
	v_max_f32_e32 v242, 0, v1
	v_exp_f32_e64 v242, -v242
	v_sub_f32_e32 v210, v210, v243
	v_sub_f32_e32 v211, v211, v243
	v_sub_f32_e32 v212, v212, v243
	v_sub_f32_e32 v213, v213, v243
	v_sub_f32_e32 v214, v214, v243
	v_sub_f32_e32 v215, v215, v243
	v_sub_f32_e32 v216, v216, v243
	v_sub_f32_e32 v217, v217, v243
	v_sub_f32_e32 v218, v218, v243
	v_sub_f32_e32 v219, v219, v243
	v_sub_f32_e32 v220, v220, v243
	v_sub_f32_e32 v221, v221, v243
	v_sub_f32_e32 v222, v222, v243
	v_sub_f32_e32 v223, v223, v243
	v_sub_f32_e32 v224, v224, v243
	v_sub_f32_e32 v225, v225, v243
	v_sub_f32_e32 v66, v66, v243
	v_sub_f32_e32 v67, v67, v243
	v_sub_f32_e32 v68, v68, v243
	v_sub_f32_e32 v69, v69, v243
	v_sub_f32_e32 v70, v70, v243
	v_sub_f32_e32 v71, v71, v243
	v_sub_f32_e32 v72, v72, v243
	v_sub_f32_e32 v73, v73, v243
	v_sub_f32_e32 v74, v74, v243
	v_sub_f32_e32 v75, v75, v243
	v_sub_f32_e32 v76, v76, v243
	v_sub_f32_e32 v77, v77, v243
	v_sub_f32_e32 v78, v78, v243
	v_sub_f32_e32 v79, v79, v243
	v_sub_f32_e32 v80, v80, v243
	v_sub_f32_e32 v81, v81, v243
	v_sub_f32_e32 v82, v82, v243
	v_sub_f32_e32 v83, v83, v243
	v_sub_f32_e32 v84, v84, v243
	v_sub_f32_e32 v85, v85, v243
	v_sub_f32_e32 v86, v86, v243
	v_sub_f32_e32 v87, v87, v243
	v_sub_f32_e32 v88, v88, v243
	v_sub_f32_e32 v89, v89, v243
	v_sub_f32_e32 v90, v90, v243
	v_sub_f32_e32 v91, v91, v243
	v_sub_f32_e32 v92, v92, v243
	v_sub_f32_e32 v93, v93, v243
	v_sub_f32_e32 v94, v94, v243
	v_sub_f32_e32 v95, v95, v243
	v_sub_f32_e32 v96, v96, v243
	v_sub_f32_e32 v97, v97, v243
	v_mul_f32_e32 v173, v173, v242
	v_pk_mul_f32 v[64:65], v[64:65], v[242:243] op_sel_hi:[1,0]
	v_pk_mul_f32 v[62:63], v[62:63], v[242:243] op_sel_hi:[1,0]
	v_pk_mul_f32 v[60:61], v[60:61], v[242:243] op_sel_hi:[1,0]
	v_pk_mul_f32 v[58:59], v[58:59], v[242:243] op_sel_hi:[1,0]
	v_pk_mul_f32 v[56:57], v[56:57], v[242:243] op_sel_hi:[1,0]
	v_pk_mul_f32 v[54:55], v[54:55], v[242:243] op_sel_hi:[1,0]
	v_pk_mul_f32 v[52:53], v[52:53], v[242:243] op_sel_hi:[1,0]
	v_pk_mul_f32 v[50:51], v[50:51], v[242:243] op_sel_hi:[1,0]
	v_pk_mul_f32 v[48:49], v[48:49], v[242:243] op_sel_hi:[1,0]
	v_pk_mul_f32 v[46:47], v[46:47], v[242:243] op_sel_hi:[1,0]
	v_pk_mul_f32 v[44:45], v[44:45], v[242:243] op_sel_hi:[1,0]
	v_pk_mul_f32 v[42:43], v[42:43], v[242:243] op_sel_hi:[1,0]
	v_pk_mul_f32 v[40:41], v[40:41], v[242:243] op_sel_hi:[1,0]
	v_pk_mul_f32 v[38:39], v[38:39], v[242:243] op_sel_hi:[1,0]
	v_pk_mul_f32 v[36:37], v[36:37], v[242:243] op_sel_hi:[1,0]
	v_pk_mul_f32 v[34:35], v[34:35], v[242:243] op_sel_hi:[1,0]
	v_pk_mul_f32 v[32:33], v[32:33], v[242:243] op_sel_hi:[1,0]
	v_pk_mul_f32 v[30:31], v[30:31], v[242:243] op_sel_hi:[1,0]
	v_pk_mul_f32 v[28:29], v[28:29], v[242:243] op_sel_hi:[1,0]
	v_pk_mul_f32 v[26:27], v[26:27], v[242:243] op_sel_hi:[1,0]
	v_pk_mul_f32 v[24:25], v[24:25], v[242:243] op_sel_hi:[1,0]
	v_pk_mul_f32 v[22:23], v[22:23], v[242:243] op_sel_hi:[1,0]
	v_pk_mul_f32 v[20:21], v[20:21], v[242:243] op_sel_hi:[1,0]
	v_pk_mul_f32 v[18:19], v[18:19], v[242:243] op_sel_hi:[1,0]
	v_pk_mul_f32 v[16:17], v[16:17], v[242:243] op_sel_hi:[1,0]
	v_pk_mul_f32 v[14:15], v[14:15], v[242:243] op_sel_hi:[1,0]
	v_pk_mul_f32 v[12:13], v[12:13], v[242:243] op_sel_hi:[1,0]
	v_pk_mul_f32 v[10:11], v[10:11], v[242:243] op_sel_hi:[1,0]
	v_pk_mul_f32 v[8:9], v[8:9], v[242:243] op_sel_hi:[1,0]
	v_pk_mul_f32 v[6:7], v[6:7], v[242:243] op_sel_hi:[1,0]
	v_pk_mul_f32 v[4:5], v[4:5], v[242:243] op_sel_hi:[1,0]
	v_pk_mul_f32 v[2:3], v[2:3], v[242:243] op_sel_hi:[1,0]
.Latt_common0:
	v_exp_f32_e32 v82, v82
	v_exp_f32_e32 v83, v83
	v_exp_f32_e32 v84, v84
	v_add_f32_e32 v173, v173, v82
	v_exp_f32_e32 v85, v85
	v_mov_b32_e32 v242, v83
	v_cvt_pk_bf16_f32 v82, v82, v83
	v_exp_f32_e32 v86, v86
	v_add_f32_e32 v173, v173, v84
	v_exp_f32_e32 v87, v87
	v_add_f32_e32 v242, v242, v85
	v_cvt_pk_bf16_f32 v83, v84, v85
	v_exp_f32_e32 v88, v88
	v_add_f32_e32 v173, v173, v86
	v_exp_f32_e32 v89, v89
	v_add_f32_e32 v242, v242, v87
	v_cvt_pk_bf16_f32 v84, v86, v87
	v_add_f32_e32 v173, v173, v88
	v_add_f32_e32 v242, v242, v89
	v_cvt_pk_bf16_f32 v85, v88, v89
	ds_read_b64_tr_b16 v[238:239], v188 offset:0x1000
	ds_read_b64_tr_b16 v[240:241], v189 offset:0x1000
	ds_read_b64_tr_b16 v[234:235], v192 offset:0x1000
	ds_read_b64_tr_b16 v[236:237], v193 offset:0x1000
	ds_read_b64_tr_b16 v[230:231], v194 offset:0x1000
	ds_read_b64_tr_b16 v[232:233], v195 offset:0x1000
	ds_read_b64_tr_b16 v[226:227], v196 offset:0x1000
	ds_read_b64_tr_b16 v[228:229], v197 offset:0x1000
	s_waitcnt lgkmcnt(8)
	v_mfma_f32_32x32x16_bf16 v[50:65], v[158:161], v[82:85], v[50:65]
	v_exp_f32_e32 v90, v90
	v_exp_f32_e32 v91, v91
	v_exp_f32_e32 v92, v92
	v_add_f32_e32 v173, v173, v90
	v_exp_f32_e32 v93, v93
	v_mfma_f32_32x32x16_bf16 v[34:49], v[154:157], v[82:85], v[34:49]
	v_add_f32_e32 v242, v242, v91
	v_cvt_pk_bf16_f32 v90, v90, v91
	v_exp_f32_e32 v94, v94
	v_add_f32_e32 v173, v173, v92
	v_exp_f32_e32 v95, v95
	v_mfma_f32_32x32x16_bf16 v[18:33], v[150:153], v[82:85], v[18:33]
	v_add_f32_e32 v242, v242, v93
	v_cvt_pk_bf16_f32 v91, v92, v93
	v_exp_f32_e32 v96, v96
	v_add_f32_e32 v173, v173, v94
	v_exp_f32_e32 v97, v97
	v_mfma_f32_32x32x16_bf16 v[2:17], v[146:149], v[82:85], v[2:17]
	v_add_f32_e32 v242, v242, v95
	v_cvt_pk_bf16_f32 v92, v94, v95
	v_add_f32_e32 v173, v173, v96
	v_add_f32_e32 v242, v242, v97
	v_cvt_pk_bf16_f32 v93, v96, v97
	ds_read_b64_tr_b16 v[158:159], v188 offset:0x2000
	ds_read_b64_tr_b16 v[160:161], v189 offset:0x2000
	ds_read_b64_tr_b16 v[154:155], v192 offset:0x2000
	ds_read_b64_tr_b16 v[156:157], v193 offset:0x2000
	ds_read_b64_tr_b16 v[150:151], v194 offset:0x2000
	ds_read_b64_tr_b16 v[152:153], v195 offset:0x2000
	ds_read_b64_tr_b16 v[146:147], v196 offset:0x2000
	ds_read_b64_tr_b16 v[148:149], v197 offset:0x2000
	s_waitcnt lgkmcnt(8)
	v_mfma_f32_32x32x16_bf16 v[50:65], v[238:241], v[90:93], v[50:65]
	v_exp_f32_e32 v66, v66
	v_exp_f32_e32 v67, v67
	v_exp_f32_e32 v68, v68
	v_add_f32_e32 v173, v173, v66
	v_exp_f32_e32 v69, v69
	v_mfma_f32_32x32x16_bf16 v[34:49], v[234:237], v[90:93], v[34:49]
	v_add_f32_e32 v242, v242, v67
	v_cvt_pk_bf16_f32 v66, v66, v67
	v_exp_f32_e32 v70, v70
	v_add_f32_e32 v173, v173, v68
	v_exp_f32_e32 v71, v71
	v_mfma_f32_32x32x16_bf16 v[18:33], v[230:233], v[90:93], v[18:33]
	v_add_f32_e32 v242, v242, v69
	v_cvt_pk_bf16_f32 v67, v68, v69
	v_exp_f32_e32 v72, v72
	v_add_f32_e32 v173, v173, v70
	v_exp_f32_e32 v73, v73
	v_mfma_f32_32x32x16_bf16 v[2:17], v[226:229], v[90:93], v[2:17]
	v_add_f32_e32 v242, v242, v71
	v_cvt_pk_bf16_f32 v68, v70, v71
	v_add_f32_e32 v173, v173, v72
	v_add_f32_e32 v242, v242, v73
	v_cvt_pk_bf16_f32 v69, v72, v73
	ds_read_b64_tr_b16 v[238:239], v188 offset:0x3000
	ds_read_b64_tr_b16 v[240:241], v189 offset:0x3000
	ds_read_b64_tr_b16 v[234:235], v192 offset:0x3000
	ds_read_b64_tr_b16 v[236:237], v193 offset:0x3000
	ds_read_b64_tr_b16 v[230:231], v194 offset:0x3000
	ds_read_b64_tr_b16 v[232:233], v195 offset:0x3000
	ds_read_b64_tr_b16 v[226:227], v196 offset:0x3000
	ds_read_b64_tr_b16 v[228:229], v197 offset:0x3000
	s_waitcnt lgkmcnt(8)
	v_mfma_f32_32x32x16_bf16 v[50:65], v[158:161], v[66:69], v[50:65]
	v_exp_f32_e32 v74, v74
	v_exp_f32_e32 v75, v75
	v_exp_f32_e32 v76, v76
	v_add_f32_e32 v173, v173, v74
	v_exp_f32_e32 v77, v77
	v_mfma_f32_32x32x16_bf16 v[34:49], v[154:157], v[66:69], v[34:49]
	v_add_f32_e32 v242, v242, v75
	v_cvt_pk_bf16_f32 v74, v74, v75
	v_exp_f32_e32 v78, v78
	v_add_f32_e32 v173, v173, v76
	v_exp_f32_e32 v79, v79
	v_mfma_f32_32x32x16_bf16 v[18:33], v[150:153], v[66:69], v[18:33]
	v_add_f32_e32 v242, v242, v77
	v_cvt_pk_bf16_f32 v75, v76, v77
	v_exp_f32_e32 v80, v80
	v_add_f32_e32 v173, v173, v78
	v_exp_f32_e32 v81, v81
	v_mfma_f32_32x32x16_bf16 v[2:17], v[146:149], v[66:69], v[2:17]
	v_add_f32_e32 v242, v242, v79
	v_cvt_pk_bf16_f32 v76, v78, v79
	v_add_f32_e32 v173, v173, v80
	v_add_f32_e32 v242, v242, v81
	v_cvt_pk_bf16_f32 v77, v80, v81
	s_waitcnt lgkmcnt(0)
	v_add_f32_e32 v173, v173, v242
	v_mfma_f32_32x32x16_bf16 v[50:65], v[238:241], v[74:77], v[50:65]
	v_mfma_f32_32x32x16_bf16 v[34:49], v[234:237], v[74:77], v[34:49]
	v_mfma_f32_32x32x16_bf16 v[18:33], v[230:233], v[74:77], v[18:33]
	v_mfma_f32_32x32x16_bf16 v[2:17], v[226:229], v[74:77], v[2:17]

.LBB0_890:
	v_cmp_lt_u32_e32 vcc, s57, v207
	s_and_saveexec_b64 s[14:15], vcc
	s_cbranch_execz .LBB0_883
	ds_read_b128 v[146:149], v198 offset:24576
	ds_read_b128 v[150:153], v198 offset:32768
	v_xor_b32_e32 v209, 0x20, v198
	ds_read_b128 v[246:249], v209 offset:24576
	ds_read_b128 v[250:253], v209 offset:32768
	v_xor_b32_e32 v190, 0x40, v198
	ds_read_b128 v[180:183], v190 offset:24576
	ds_read_b128 v[184:187], v190 offset:32768
	s_waitcnt lgkmcnt(4)
	v_mfma_f32_32x32x16_bf16 v[82:97], v[146:149], v[98:101], v[210:225]
	v_mfma_f32_32x32x16_bf16 v[66:81], v[150:153], v[98:101], v[210:225]
	v_xor_b32_e32 v209, 0x60, v198
	ds_read_b128 v[146:149], v209 offset:24576
	ds_read_b128 v[150:153], v209 offset:32768
	s_waitcnt lgkmcnt(4)
	v_mfma_f32_32x32x16_bf16 v[82:97], v[246:249], v[102:105], v[82:97]
	v_mfma_f32_32x32x16_bf16 v[66:81], v[250:253], v[102:105], v[66:81]
	v_xor_b32_e32 v190, 0x80, v198
	ds_read_b128 v[246:249], v190 offset:24576
	ds_read_b128 v[250:253], v190 offset:32768
	s_waitcnt lgkmcnt(4)
	v_mfma_f32_32x32x16_bf16 v[82:97], v[180:183], v[106:109], v[82:97]
	v_mfma_f32_32x32x16_bf16 v[66:81], v[184:187], v[106:109], v[66:81]
	v_xor_b32_e32 v209, 0xa0, v198
	ds_read_b128 v[180:183], v209 offset:24576
	ds_read_b128 v[184:187], v209 offset:32768
	s_waitcnt lgkmcnt(4)
	v_mfma_f32_32x32x16_bf16 v[82:97], v[146:149], v[110:113], v[82:97]
	v_mfma_f32_32x32x16_bf16 v[66:81], v[150:153], v[110:113], v[66:81]
	v_xor_b32_e32 v190, 0xc0, v198
	ds_read_b128 v[146:149], v190 offset:24576
	ds_read_b128 v[150:153], v190 offset:32768
	s_waitcnt lgkmcnt(4)
	v_mfma_f32_32x32x16_bf16 v[82:97], v[246:249], v[122:125], v[82:97]
	v_mfma_f32_32x32x16_bf16 v[66:81], v[250:253], v[122:125], v[66:81]
	v_xor_b32_e32 v209, 0xe0, v198
	ds_read_b128 v[246:249], v209 offset:24576
	ds_read_b128 v[250:253], v209 offset:32768
	s_waitcnt lgkmcnt(4)
	v_mfma_f32_32x32x16_bf16 v[82:97], v[180:183], v[114:117], v[82:97]
	v_mfma_f32_32x32x16_bf16 v[66:81], v[184:187], v[114:117], v[66:81]
	ds_read_b128 v[180:183], v199 offset:24576
	ds_read_b128 v[184:187], v199 offset:28672
	s_waitcnt lgkmcnt(4)
	v_mfma_f32_32x32x16_bf16 v[82:97], v[146:149], v[118:121], v[82:97]
	v_mfma_f32_32x32x16_bf16 v[66:81], v[150:153], v[118:121], v[66:81]
	v_xor_b32_e32 v209, 0x20, v199
	ds_read_b128 v[146:149], v209 offset:24576
	ds_read_b128 v[150:153], v209 offset:28672
	s_waitcnt lgkmcnt(4)
	v_mfma_f32_32x32x16_bf16 v[82:97], v[246:249], v[126:129], v[82:97]
	v_mfma_f32_32x32x16_bf16 v[66:81], v[250:253], v[126:129], v[66:81]
	v_xor_b32_e32 v190, 0x40, v199
	ds_read_b128 v[246:249], v190 offset:24576
	ds_read_b128 v[250:253], v190 offset:28672
	s_waitcnt lgkmcnt(4)
	v_mfma_f32_32x32x16_bf16 v[82:97], v[180:183], v[130:133], v[82:97]
	v_mfma_f32_32x32x16_bf16 v[66:81], v[184:187], v[130:133], v[66:81]
	v_xor_b32_e32 v209, 0x60, v199
	ds_read_b128 v[180:183], v209 offset:24576
	ds_read_b128 v[184:187], v209 offset:28672
	s_waitcnt lgkmcnt(4)
	v_mfma_f32_32x32x16_bf16 v[82:97], v[146:149], v[134:137], v[82:97]
	v_mfma_f32_32x32x16_bf16 v[66:81], v[150:153], v[134:137], v[66:81]
	s_waitcnt lgkmcnt(2)
	v_mfma_f32_32x32x16_bf16 v[82:97], v[246:249], v[138:141], v[82:97]
	v_mfma_f32_32x32x16_bf16 v[66:81], v[250:253], v[138:141], v[66:81]
	s_waitcnt lgkmcnt(0)
	v_mfma_f32_32x32x16_bf16 v[66:81], v[184:187], v[142:145], v[66:81]
	ds_read_b64_tr_b16 v[158:159], v188 offset:0x6000
	ds_read_b64_tr_b16 v[160:161], v189 offset:0x6000
	ds_read_b64_tr_b16 v[154:155], v192 offset:0x6000
	ds_read_b64_tr_b16 v[156:157], v193 offset:0x6000
	ds_read_b64_tr_b16 v[150:151], v194 offset:0x6000
	ds_read_b64_tr_b16 v[152:153], v195 offset:0x6000
	ds_read_b64_tr_b16 v[146:147], v196 offset:0x6000
	ds_read_b64_tr_b16 v[148:149], v197 offset:0x6000
	v_mfma_f32_32x32x16_bf16 v[82:97], v[180:183], v[142:145], v[82:97]
	s_nop 4
	v_max3_f32 v1, v66, v67, v68
	v_max3_f32 v180, v69, v70, v71
	v_max3_f32 v1, v1, v72, v73
	v_max3_f32 v180, v180, v74, v75
	v_max3_f32 v1, v1, v76, v77
	v_max3_f32 v180, v180, v78, v79
	v_max3_f32 v1, v1, v80, v81
	v_max3_f32 v181, v82, v83, v84
	v_max3_f32 v182, v85, v86, v87
	v_max3_f32 v181, v181, v88, v89
	v_max3_f32 v182, v182, v90, v91
	v_max3_f32 v181, v181, v92, v93
	v_max3_f32 v182, v182, v94, v95
	v_max3_f32 v181, v181, v96, v97
	v_max3_f32 v1, v1, v180, v181
	v_max_f32_e32 v1, v1, v182
	v_mov_b32_e32 v180, v1
	s_nop 1
	v_permlane32_swap_b32_e32 v1, v180
	v_max_f32_e32 v1, v1, v180
	v_cmp_lt_f32_e32 vcc, 0x41000000, v1
	s_cbranch_vccz .Latt_common1
.Latt_rare1:
	v_max_f32_e32 v243, 0, v1
	v_max_f32_e32 v242, 0, v1
	v_exp_f32_e64 v242, -v242
	v_sub_f32_e32 v210, v210, v243
	v_sub_f32_e32 v211, v211, v243
	v_sub_f32_e32 v212, v212, v243
	v_sub_f32_e32 v213, v213, v243
	v_sub_f32_e32 v214, v214, v243
	v_sub_f32_e32 v215, v215, v243
	v_sub_f32_e32 v216, v216, v243
	v_sub_f32_e32 v217, v217, v243
	v_sub_f32_e32 v218, v218, v243
	v_sub_f32_e32 v219, v219, v243
	v_sub_f32_e32 v220, v220, v243
	v_sub_f32_e32 v221, v221, v243
	v_sub_f32_e32 v222, v222, v243
	v_sub_f32_e32 v223, v223, v243
	v_sub_f32_e32 v224, v224, v243
	v_sub_f32_e32 v225, v225, v243
	v_sub_f32_e32 v66, v66, v243
	v_sub_f32_e32 v67, v67, v243
	v_sub_f32_e32 v68, v68, v243
	v_sub_f32_e32 v69, v69, v243
	v_sub_f32_e32 v70, v70, v243
	v_sub_f32_e32 v71, v71, v243
	v_sub_f32_e32 v72, v72, v243
	v_sub_f32_e32 v73, v73, v243
	v_sub_f32_e32 v74, v74, v243
	v_sub_f32_e32 v75, v75, v243
	v_sub_f32_e32 v76, v76, v243
	v_sub_f32_e32 v77, v77, v243
	v_sub_f32_e32 v78, v78, v243
	v_sub_f32_e32 v79, v79, v243
	v_sub_f32_e32 v80, v80, v243
	v_sub_f32_e32 v81, v81, v243
	v_sub_f32_e32 v82, v82, v243
	v_sub_f32_e32 v83, v83, v243
	v_sub_f32_e32 v84, v84, v243
	v_sub_f32_e32 v85, v85, v243
	v_sub_f32_e32 v86, v86, v243
	v_sub_f32_e32 v87, v87, v243
	v_sub_f32_e32 v88, v88, v243
	v_sub_f32_e32 v89, v89, v243
	v_sub_f32_e32 v90, v90, v243
	v_sub_f32_e32 v91, v91, v243
	v_sub_f32_e32 v92, v92, v243
	v_sub_f32_e32 v93, v93, v243
	v_sub_f32_e32 v94, v94, v243
	v_sub_f32_e32 v95, v95, v243
	v_sub_f32_e32 v96, v96, v243
	v_sub_f32_e32 v97, v97, v243
	v_mul_f32_e32 v173, v173, v242
	v_pk_mul_f32 v[64:65], v[64:65], v[242:243] op_sel_hi:[1,0]
	v_pk_mul_f32 v[62:63], v[62:63], v[242:243] op_sel_hi:[1,0]
	v_pk_mul_f32 v[60:61], v[60:61], v[242:243] op_sel_hi:[1,0]
	v_pk_mul_f32 v[58:59], v[58:59], v[242:243] op_sel_hi:[1,0]
	v_pk_mul_f32 v[56:57], v[56:57], v[242:243] op_sel_hi:[1,0]
	v_pk_mul_f32 v[54:55], v[54:55], v[242:243] op_sel_hi:[1,0]
	v_pk_mul_f32 v[52:53], v[52:53], v[242:243] op_sel_hi:[1,0]
	v_pk_mul_f32 v[50:51], v[50:51], v[242:243] op_sel_hi:[1,0]
	v_pk_mul_f32 v[48:49], v[48:49], v[242:243] op_sel_hi:[1,0]
	v_pk_mul_f32 v[46:47], v[46:47], v[242:243] op_sel_hi:[1,0]
	v_pk_mul_f32 v[44:45], v[44:45], v[242:243] op_sel_hi:[1,0]
	v_pk_mul_f32 v[42:43], v[42:43], v[242:243] op_sel_hi:[1,0]
	v_pk_mul_f32 v[40:41], v[40:41], v[242:243] op_sel_hi:[1,0]
	v_pk_mul_f32 v[38:39], v[38:39], v[242:243] op_sel_hi:[1,0]
	v_pk_mul_f32 v[36:37], v[36:37], v[242:243] op_sel_hi:[1,0]
	v_pk_mul_f32 v[34:35], v[34:35], v[242:243] op_sel_hi:[1,0]
	v_pk_mul_f32 v[32:33], v[32:33], v[242:243] op_sel_hi:[1,0]
	v_pk_mul_f32 v[30:31], v[30:31], v[242:243] op_sel_hi:[1,0]
	v_pk_mul_f32 v[28:29], v[28:29], v[242:243] op_sel_hi:[1,0]
	v_pk_mul_f32 v[26:27], v[26:27], v[242:243] op_sel_hi:[1,0]
	v_pk_mul_f32 v[24:25], v[24:25], v[242:243] op_sel_hi:[1,0]
	v_pk_mul_f32 v[22:23], v[22:23], v[242:243] op_sel_hi:[1,0]
	v_pk_mul_f32 v[20:21], v[20:21], v[242:243] op_sel_hi:[1,0]
	v_pk_mul_f32 v[18:19], v[18:19], v[242:243] op_sel_hi:[1,0]
	v_pk_mul_f32 v[16:17], v[16:17], v[242:243] op_sel_hi:[1,0]
	v_pk_mul_f32 v[14:15], v[14:15], v[242:243] op_sel_hi:[1,0]
	v_pk_mul_f32 v[12:13], v[12:13], v[242:243] op_sel_hi:[1,0]
	v_pk_mul_f32 v[10:11], v[10:11], v[242:243] op_sel_hi:[1,0]
	v_pk_mul_f32 v[8:9], v[8:9], v[242:243] op_sel_hi:[1,0]
	v_pk_mul_f32 v[6:7], v[6:7], v[242:243] op_sel_hi:[1,0]
	v_pk_mul_f32 v[4:5], v[4:5], v[242:243] op_sel_hi:[1,0]
	v_pk_mul_f32 v[2:3], v[2:3], v[242:243] op_sel_hi:[1,0]
.Latt_common1:
	v_exp_f32_e32 v82, v82
	v_exp_f32_e32 v83, v83
	v_exp_f32_e32 v84, v84
	v_add_f32_e32 v173, v173, v82
	v_exp_f32_e32 v85, v85
	v_mov_b32_e32 v242, v83
	v_cvt_pk_bf16_f32 v82, v82, v83
	v_exp_f32_e32 v86, v86
	v_add_f32_e32 v173, v173, v84
	v_exp_f32_e32 v87, v87
	v_add_f32_e32 v242, v242, v85
	v_cvt_pk_bf16_f32 v83, v84, v85
	v_exp_f32_e32 v88, v88
	v_add_f32_e32 v173, v173, v86
	v_exp_f32_e32 v89, v89
	v_add_f32_e32 v242, v242, v87
	v_cvt_pk_bf16_f32 v84, v86, v87
	v_add_f32_e32 v173, v173, v88
	v_add_f32_e32 v242, v242, v89
	v_cvt_pk_bf16_f32 v85, v88, v89
	ds_read_b64_tr_b16 v[238:239], v188 offset:0x7000
	ds_read_b64_tr_b16 v[240:241], v189 offset:0x7000
	ds_read_b64_tr_b16 v[234:235], v192 offset:0x7000
	ds_read_b64_tr_b16 v[236:237], v193 offset:0x7000
	ds_read_b64_tr_b16 v[230:231], v194 offset:0x7000
	ds_read_b64_tr_b16 v[232:233], v195 offset:0x7000
	ds_read_b64_tr_b16 v[226:227], v196 offset:0x7000
	ds_read_b64_tr_b16 v[228:229], v197 offset:0x7000
	s_waitcnt lgkmcnt(8)
	v_mfma_f32_32x32x16_bf16 v[50:65], v[158:161], v[82:85], v[50:65]
	v_exp_f32_e32 v90, v90
	v_exp_f32_e32 v91, v91
	v_exp_f32_e32 v92, v92
	v_add_f32_e32 v173, v173, v90
	v_exp_f32_e32 v93, v93
	v_mfma_f32_32x32x16_bf16 v[34:49], v[154:157], v[82:85], v[34:49]
	v_add_f32_e32 v242, v242, v91
	v_cvt_pk_bf16_f32 v90, v90, v91
	v_exp_f32_e32 v94, v94
	v_add_f32_e32 v173, v173, v92
	v_exp_f32_e32 v95, v95
	v_mfma_f32_32x32x16_bf16 v[18:33], v[150:153], v[82:85], v[18:33]
	v_add_f32_e32 v242, v242, v93
	v_cvt_pk_bf16_f32 v91, v92, v93
	v_exp_f32_e32 v96, v96
	v_add_f32_e32 v173, v173, v94
	v_exp_f32_e32 v97, v97
	v_mfma_f32_32x32x16_bf16 v[2:17], v[146:149], v[82:85], v[2:17]
	v_add_f32_e32 v242, v242, v95
	v_cvt_pk_bf16_f32 v92, v94, v95
	v_add_f32_e32 v173, v173, v96
	v_add_f32_e32 v242, v242, v97
	v_cvt_pk_bf16_f32 v93, v96, v97
	ds_read_b64_tr_b16 v[158:159], v188 offset:0x8000
	ds_read_b64_tr_b16 v[160:161], v189 offset:0x8000
	ds_read_b64_tr_b16 v[154:155], v192 offset:0x8000
	ds_read_b64_tr_b16 v[156:157], v193 offset:0x8000
	ds_read_b64_tr_b16 v[150:151], v194 offset:0x8000
	ds_read_b64_tr_b16 v[152:153], v195 offset:0x8000
	ds_read_b64_tr_b16 v[146:147], v196 offset:0x8000
	ds_read_b64_tr_b16 v[148:149], v197 offset:0x8000
	s_waitcnt lgkmcnt(8)
	v_mfma_f32_32x32x16_bf16 v[50:65], v[238:241], v[90:93], v[50:65]
	v_exp_f32_e32 v66, v66
	v_exp_f32_e32 v67, v67
	v_exp_f32_e32 v68, v68
	v_add_f32_e32 v173, v173, v66
	v_exp_f32_e32 v69, v69
	v_mfma_f32_32x32x16_bf16 v[34:49], v[234:237], v[90:93], v[34:49]
	v_add_f32_e32 v242, v242, v67
	v_cvt_pk_bf16_f32 v66, v66, v67
	v_exp_f32_e32 v70, v70
	v_add_f32_e32 v173, v173, v68
	v_exp_f32_e32 v71, v71
	v_mfma_f32_32x32x16_bf16 v[18:33], v[230:233], v[90:93], v[18:33]
	v_add_f32_e32 v242, v242, v69
	v_cvt_pk_bf16_f32 v67, v68, v69
	v_exp_f32_e32 v72, v72
	v_add_f32_e32 v173, v173, v70
	v_exp_f32_e32 v73, v73
	v_mfma_f32_32x32x16_bf16 v[2:17], v[226:229], v[90:93], v[2:17]
	v_add_f32_e32 v242, v242, v71
	v_cvt_pk_bf16_f32 v68, v70, v71
	v_add_f32_e32 v173, v173, v72
	v_add_f32_e32 v242, v242, v73
	v_cvt_pk_bf16_f32 v69, v72, v73
	ds_read_b64_tr_b16 v[238:239], v188 offset:0x9000
	ds_read_b64_tr_b16 v[240:241], v189 offset:0x9000
	ds_read_b64_tr_b16 v[234:235], v192 offset:0x9000
	ds_read_b64_tr_b16 v[236:237], v193 offset:0x9000
	ds_read_b64_tr_b16 v[230:231], v194 offset:0x9000
	ds_read_b64_tr_b16 v[232:233], v195 offset:0x9000
	ds_read_b64_tr_b16 v[226:227], v196 offset:0x9000
	ds_read_b64_tr_b16 v[228:229], v197 offset:0x9000
	s_waitcnt lgkmcnt(8)
	v_mfma_f32_32x32x16_bf16 v[50:65], v[158:161], v[66:69], v[50:65]
	v_exp_f32_e32 v74, v74
	v_exp_f32_e32 v75, v75
	v_exp_f32_e32 v76, v76
	v_add_f32_e32 v173, v173, v74
	v_exp_f32_e32 v77, v77
	v_mfma_f32_32x32x16_bf16 v[34:49], v[154:157], v[66:69], v[34:49]
	v_add_f32_e32 v242, v242, v75
	v_cvt_pk_bf16_f32 v74, v74, v75
	v_exp_f32_e32 v78, v78
	v_add_f32_e32 v173, v173, v76
	v_exp_f32_e32 v79, v79
	v_mfma_f32_32x32x16_bf16 v[18:33], v[150:153], v[66:69], v[18:33]
	v_add_f32_e32 v242, v242, v77
	v_cvt_pk_bf16_f32 v75, v76, v77
	v_exp_f32_e32 v80, v80
	v_add_f32_e32 v173, v173, v78
	v_exp_f32_e32 v81, v81
	v_mfma_f32_32x32x16_bf16 v[2:17], v[146:149], v[66:69], v[2:17]
	v_add_f32_e32 v242, v242, v79
	v_cvt_pk_bf16_f32 v76, v78, v79
	v_add_f32_e32 v173, v173, v80
	v_add_f32_e32 v242, v242, v81
	v_cvt_pk_bf16_f32 v77, v80, v81
	s_waitcnt lgkmcnt(0)
	v_add_f32_e32 v173, v173, v242
	v_mfma_f32_32x32x16_bf16 v[50:65], v[238:241], v[74:77], v[50:65]
	v_mfma_f32_32x32x16_bf16 v[34:49], v[234:237], v[74:77], v[34:49]
	v_mfma_f32_32x32x16_bf16 v[18:33], v[230:233], v[74:77], v[18:33]
	v_mfma_f32_32x32x16_bf16 v[2:17], v[226:229], v[74:77], v[2:17]
	s_branch .LBB0_883
